# v32 + phase-start row-scale prep (G1/G3/G5) moved behind the first-stage LDS-DMA issues, registers renamed into dead accumulators: the two start-up memory round trips overlap
# speedup vs baseline: 1.0027x; 1.0002x over previous
; __device__ __forceinline__ void rs_prep(const float* ss, int pm, int parity, PG8_LAS unsigned char* lds, int tid) {
;     if (tid < 256) {
;         const f32x4* p = (const f32x4*)(ss + (size_t)(pm * BM + tid) * 32);
;         f32x4 s = p[0];
; #pragma unroll
;         for (int j = 1; j < 8; ++j) s += p[j];
;         const float tot = (s[0] + s[1]) + (s[2] + s[3]);
;         *(PG8_LAS float*)(lds + RS_OFF + parity * 1024 + tid * 4) = __builtin_amdgcn_rsqf(tot * (1.0f / 2048.0f) + 1e-6f);
;     }
;     asm volatile("s_waitcnt lgkmcnt(0)" ::: "memory");
; }
; template <class Epi, class Sched, bool ALIGN_EPI = false, bool SP2 = false>
; __device__ __forceinline__ void gemm_phase(PG8_LAS unsigned char* lds, const Gemm g, const Sched& S, const Epi& E, const int wave_id) {
;     ...
;     for (int i = 0; i < 2; ++i) { int R, C; stage_rc(tid * 16 + i * 8192, R, C); const int Rb = Epi::PERM ? ((R & ~31) + perm32(R & 31)) : R;
;         voffA[i] = (unsigned)(R * K + C) * 2u; voffB[i] = (unsigned)(Rb * K + C) * 2u; }
;     const size_t kstep = (size_t)(BK * 2);
;     const size_t hstep = (size_t)HALF * K * 2;
;     const size_t tstep = 2 * hstep;
;     const unsigned ldsw = (unsigned)wid * 1024u;
;     const int aoff = lds_byte(wr * 64 + fr, fq * 8), boff = lds_byte(wc * 32 + fr, fq * 8);
;     ...
;     Unit cur, nxt; int ui = 0, tp = 0;
;     if (!S.next(0, cur)) return;
;     f32x4 acc[2][2][4][2];
; #pragma unroll
;     for (int a = 0; a < 2; ++a)
; #pragma unroll
;         for (int b = 0; b < 2; ++b)
; #pragma unroll
;             for (int m = 0; m < 4; ++m)
; #pragma unroll
;                 for (int n = 0; n < 2; ++n) acc[a][b][m][n] = (f32x4){0.f, 0.f, 0.f, 0.f};
;     bf16x8 At[4][2], B0[2][2], B1[2][2];
;     const char* cA = (const char*)g.A + (size_t)cur.lm * tstep; const char* cB = (const char*)g.Bt + (size_t)cur.ln * tstep;
;     if constexpr (Epi::HAS_PREP) E.prep(cur, 0, lds, tid);
;     S.a_ready(cur);
;     if constexpr (SP2) {
;         PG8_STAGE(PG8_SB(0, 0), cB, voffB); PG8_STAGE(PG8_SB(0, 1), cB + hstep, voffB); PG8_STAGE(PG8_SA(0, 0), cA, voffA); PG8_STAGE(PG8_SA(0, 1), cA + hstep, voffA);
;         if (wr == 1) PG8_BAR;
;         PG8_WAIT_V(2); PG8_BAR;
;         PG8_STAGE(PG8_SB(1, 0), cB + kstep, voffB); PG8_STAGE(PG8_SA(1, 0), cA + kstep, voffA); PG8_STAGE(PG8_SB(1, 1), cB + hstep + kstep, voffB);
;         PG8_WAIT_V(6); PG8_BAR;
.LBB0_159:
	s_andn2_b64 vcc, exec, s[2:3]
	s_cbranch_vccnz .LBB0_230
	s_add_u32 s2, s8, 0x200000
	v_lshl_add_u32 v1, s14, 6, v10
	s_movk_i32 s12, 0x100
	s_addc_u32 s3, s9, 0
	v_cmp_gt_i32_e64 s[36:37], s12, v1
	v_ashrrev_i32_e32 v3, 31, v1
	v_lshrrev_b32_e32 v3, 26, v3
	v_add_u32_e32 v3, v1, v3
	v_ashrrev_i32_e32 v11, 6, v3
	v_bfe_i32 v3, v1, 27, 1
	v_lshlrev_b32_e32 v2, 4, v1
	v_lshrrev_b32_e32 v3, 22, v3
	v_add_u32_e32 v3, v2, v3
	v_and_b32_e32 v3, 0xfffffc00, v3
	v_sub_u32_e32 v3, v2, v3
	v_lshrrev_b32_e32 v4, 4, v3
	v_bitop3_b32 v3, v4, v3, 32 bitop3:0x6c
	v_ashrrev_i32_e32 v5, 31, v3
	v_lshrrev_b32_e32 v5, 26, v5
	v_add_u32_e32 v5, v3, v5
	v_lshlrev_b32_e32 v4, 3, v11
	v_ashrrev_i32_e32 v12, 6, v5
	v_and_b32_e32 v5, 0xc0, v5
	v_and_b32_e32 v4, -16, v4
	v_sub_u32_e32 v3, v3, v5
	v_add_u32_e32 v4, v12, v4
	v_ashrrev_i16_sdwa v3, v223, sext(v3) dst_sel:DWORD dst_unused:UNUSED_PAD src0_sel:DWORD src1_sel:BYTE_0
	v_lshlrev_b32_e32 v6, 5, v11
	v_bfe_i32 v13, v3, 0, 16
	v_lshlrev_b32_e32 v3, 1, v4
	v_lshrrev_b32_e32 v5, 2, v4
	v_and_b32_e32 v7, 3, v12
	s_mov_b32 s19, 0xfffe0
	v_and_b32_e32 v6, 32, v6
	v_and_b32_e32 v3, 24, v3
	v_and_b32_e32 v5, 4, v5
	v_and_or_b32 v7, v4, s19, v7
	v_readlane_b32 s16, v252, 15
	v_or3_b32 v3, v7, v5, v3
	v_add_lshl_u32 v5, v6, v13, 1
	v_add_u32_e32 v2, 0x2000, v2
	s_mul_i32 s12, s16, 0x6300000
	v_lshl_add_u32 v132, v3, 12, v5
	v_ashrrev_i32_e32 v3, 31, v2
	s_add_u32 s12, s8, s12
	v_lshrrev_b32_e32 v3, 22, v3
	s_addc_u32 s13, s9, 0
	v_add_u32_e32 v3, v2, v3
	s_add_u32 s47, s12, 0x1000000
	v_ashrrev_i32_e32 v14, 10, v3
	s_addc_u32 s48, s13, 0
	v_mul_i32_i24_e32 v3, 0x400, v14
	s_bitcmp0_b32 s16, 0
	s_mov_b32 s12, 0x1dc00000
	v_sub_u32_e32 v2, v2, v3
	s_cselect_b32 s12, s12, 0x25c00000
	v_lshrrev_b32_e32 v3, 4, v2
	s_add_u32 s49, s8, s12
	v_bitop3_b32 v2, v3, v2, 32 bitop3:0x6c
	s_addc_u32 s52, s9, 0
	v_lshl_add_u32 v130, v4, 12, v5
	v_ashrrev_i32_e32 v4, 31, v2
	s_add_u32 s20, s49, s10
	v_lshrrev_b32_e32 v4, 26, v4
	s_addc_u32 s21, s52, s11
	v_add_u32_e32 v4, v2, v4
	s_add_u32 s42, s47, s4
	v_lshlrev_b32_e32 v3, 3, v14
	v_ashrrev_i32_e32 v15, 6, v4
	v_and_b32_e32 v4, 0xc0, v4
	s_addc_u32 s43, s48, s5
	s_ashr_i32 s12, s14, 2
	s_lshl_b32 s53, s14, 10
	v_and_b32_e32 v3, -16, v3
	v_sub_u32_e32 v2, v2, v4
	s_cmp_eq_u32 s12, 1
	v_add_u32_e32 v3, v15, v3
	v_ashrrev_i16_sdwa v2, v223, sext(v2) dst_sel:DWORD dst_unused:UNUSED_PAD src0_sel:DWORD src1_sel:BYTE_0
	s_cselect_b64 s[4:5], -1, 0
	s_add_i32 s56, s53, 0
	v_lshlrev_b32_e32 v5, 5, v14
	v_bfe_i32 v16, v2, 0, 16
	v_lshlrev_b32_e32 v2, 1, v3
	v_lshrrev_b32_e32 v4, 2, v3
	v_and_b32_e32 v6, 3, v15
	s_add_i32 m0, s56, 0x10000
	s_add_i32 s13, s56, 0x12000
	v_and_b32_e32 v5, 32, v5
	v_and_b32_e32 v2, 24, v2
	v_and_b32_e32 v4, 4, v4
	v_and_or_b32 v6, v3, s19, v6
	v_readlane_b32 s17, v252, 16
	s_add_u32 s16, s42, 0x80000
	v_or3_b32 v2, v6, v4, v2
	v_add_lshl_u32 v4, v5, v16, 1
	s_waitcnt lgkmcnt(0)
	s_addc_u32 s17, s43, 0
	s_add_i32 s15, s56, 0x14000
	v_lshl_add_u32 v136, v2, 12, v4
	global_load_lds_dwordx4 v132, s[42:43]
	s_mov_b32 m0, s13
	s_add_i32 s18, s56, 0x16000
	global_load_lds_dwordx4 v136, s[42:43]
	s_mov_b32 m0, s15
	s_add_i32 s57, s56, 0x2000
	global_load_lds_dwordx4 v132, s[16:17]
	s_mov_b32 m0, s18
	s_add_u32 s10, s20, 0x80000
	global_load_lds_dwordx4 v136, s[16:17]
	s_mov_b32 m0, s56
	s_addc_u32 s11, s21, 0
	s_add_i32 s64, s56, 0x4000
	v_lshl_add_u32 v134, v3, 12, v4
	global_load_lds_dwordx4 v130, s[20:21]
	s_mov_b32 m0, s57
	s_add_i32 s65, s56, 0x6000
	global_load_lds_dwordx4 v134, s[20:21]
	s_mov_b32 m0, s64
	v_mov_b32_e32 v133, v0
	global_load_lds_dwordx4 v130, s[10:11]
	s_mov_b32 m0, s65
	v_mov_b32_e32 v137, v0
	global_load_lds_dwordx4 v134, s[10:11]
	v_mov_b32_e32 v131, v0
	v_mov_b32_e32 v135, v0
	s_and_saveexec_b64 vcc, s[36:37]
	s_cbranch_execz .Lprep_0
	v_lshl_add_u32 v90, s40, 8, v1
	v_ashrrev_i32_e32 v91, 31, v90
	v_lshlrev_b64 v[90:91], 7, v[90:91]
	v_lshl_add_u64 v[120:121], s[2:3], 0, v[90:91]
	global_load_dwordx4 v[90:93], v[120:121], off
	global_load_dwordx4 v[94:97], v[120:121], off offset:16
	global_load_dwordx4 v[100:103], v[120:121], off offset:32
	global_load_dwordx4 v[104:107], v[120:121], off offset:48
	global_load_dwordx4 v[108:111], v[120:121], off offset:64
	global_load_dwordx4 v[112:115], v[120:121], off offset:80
	global_load_dwordx4 v[116:119], v[120:121], off offset:96
	s_nop 0
	global_load_dwordx4 v[120:123], v[120:121], off offset:112
	s_waitcnt vmcnt(0)
	v_pk_add_f32 v[92:93], v[92:93], v[96:97]
	v_pk_add_f32 v[90:91], v[90:91], v[94:95]
	s_waitcnt vmcnt(5)
	v_pk_add_f32 v[92:93], v[92:93], v[102:103]
	v_pk_add_f32 v[90:91], v[90:91], v[100:101]
	s_waitcnt vmcnt(4)
	v_pk_add_f32 v[92:93], v[92:93], v[106:107]
	v_pk_add_f32 v[90:91], v[90:91], v[104:105]
	s_waitcnt vmcnt(3)
	v_pk_add_f32 v[92:93], v[92:93], v[110:111]
	v_pk_add_f32 v[90:91], v[90:91], v[108:109]
	s_waitcnt vmcnt(2)
	v_pk_add_f32 v[92:93], v[92:93], v[114:115]
	v_pk_add_f32 v[90:91], v[90:91], v[112:113]
	s_waitcnt vmcnt(1)
	v_pk_add_f32 v[92:93], v[92:93], v[118:119]
	v_pk_add_f32 v[90:91], v[90:91], v[116:117]
	s_waitcnt vmcnt(0)
	v_pk_add_f32 v[92:93], v[92:93], v[122:123]
	v_pk_add_f32 v[90:91], v[90:91], v[120:121]
	s_nop 0
	v_pk_mov_b32 v[94:95], v[90:91], v[92:93] op_sel:[1,0]
	v_mov_b32_e32 v91, v93
	v_pk_add_f32 v[90:91], v[94:95], v[90:91]
	s_nop 0
	v_add_f32_e32 v90, v90, v91
	v_fmamk_f32 v90, v90, 0x3a000000, v221
	v_rsq_f32_e32 v90, v90
	v_lshl_add_u32 v91, v1, 2, 0
	v_add_u32_e32 v91, 0x20000, v91
	ds_write_b32 v91, v90
.Lprep_0:
	s_or_b64 exec, exec, vcc
	s_cmp_lg_u32 s12, 1
	v_lshl_add_u64 v[8:9], s[42:43], 0, v[132:133]
	v_lshl_add_u64 v[6:7], s[42:43], 0, v[136:137]
	v_lshl_add_u64 v[4:5], s[20:21], 0, v[130:131]
	v_lshl_add_u64 v[2:3], s[20:21], 0, v[134:135]
	s_cbranch_scc1 .LBB0_164
	s_barrier

;     __host__ __device__ bool next(int i, Unit& u) const { const bool ok = StaticOrder::next(i, u); u.lm = 0; u.ln = 0; return ok; }
;     __host__ __device__ bool next(int i, Unit& u) const {
;         if ((long)i * G + c >= nwg) return false;
;         const long L = rev ? (long)((nwg - 1 - c) / G - i) * G + c : (long)i * G + c;
;         int wgid = (int)L; { const int q = nwg / NXCD, r = nwg % NXCD, xcd = wgid % NXCD, off = wgid / NXCD; wgid = (xcd < r ? xcd * (q + 1) : r * (q + 1) + (xcd - r) * q) + off; }
;         const int nig = wgm * nN, gid = wgid / nig, fm = gid * wgm, gsz = (nM - fm) < wgm ? (nM - fm) : wgm;
;         u.pm = fm + ((wgid % nig) % gsz); u.pn = (wgid % nig) / gsz; u.lm = fixed ? 0 : u.pm; u.ln = fixed ? 0 : u.pn; return true;
; template <class Epi, class Sched, bool ALIGN_EPI = false, bool SP2 = false>
; __device__ __forceinline__ void gemm_phase(PG8_LAS unsigned char* lds, const Gemm g, const Sched& S, const Epi& E, const int wave_id) {
;     ...
;     for (int i = 0; i < 2; ++i) { int R, C; stage_rc(tid * 16 + i * 8192, R, C); const int Rb = Epi::PERM ? ((R & ~31) + perm32(R & 31)) : R;
;         voffA[i] = (unsigned)(R * K + C) * 2u; voffB[i] = (unsigned)(Rb * K + C) * 2u; }
;     const size_t kstep = (size_t)(BK * 2);
;     const size_t hstep = (size_t)HALF * K * 2;
;     const size_t tstep = 2 * hstep;
;     const unsigned ldsw = (unsigned)wid * 1024u;
;     const int aoff = lds_byte(wr * 64 + fr, fq * 8), boff = lds_byte(wc * 32 + fr, fq * 8);
;     ...
;     Unit cur, nxt; int ui = 0, tp = 0;
;     if (!S.next(0, cur)) return;
;     f32x4 acc[2][2][4][2];
; #pragma unroll
;     for (int a = 0; a < 2; ++a)
; #pragma unroll
;         for (int b = 0; b < 2; ++b)
; #pragma unroll
;             for (int m = 0; m < 4; ++m)
; #pragma unroll
;                 for (int n = 0; n < 2; ++n) acc[a][b][m][n] = (f32x4){0.f, 0.f, 0.f, 0.f};
;     bf16x8 At[4][2], B0[2][2], B1[2][2];
;     const char* cA = (const char*)g.A + (size_t)cur.lm * tstep; const char* cB = (const char*)g.Bt + (size_t)cur.ln * tstep;
;     if constexpr (Epi::HAS_PREP) E.prep(cur, 0, lds, tid);
;     S.a_ready(cur);
;     if constexpr (SP2) {
;         PG8_STAGE(PG8_SB(0, 0), cB, voffB); PG8_STAGE(PG8_SB(0, 1), cB + hstep, voffB); PG8_STAGE(PG8_SA(0, 0), cA, voffA); PG8_STAGE(PG8_SA(0, 1), cA + hstep, voffA);
;         if (wr == 1) PG8_BAR;
;         PG8_WAIT_V(2); PG8_BAR;
.LBB0_629:
	s_andn2_b64 vcc, exec, s[2:3]
	s_cbranch_vccnz .LBB0_733
	v_readlane_b32 s2, v253, 50
	v_readlane_b32 s12, v254, 63
	v_readlane_b32 s3, v253, 51
	v_readlane_b32 s13, v252, 0
	v_readlane_b32 s14, v252, 1
	v_readlane_b32 s15, v252, 2
	s_mov_b32 s4, s2
	s_mov_b64 s[2:3], s[12:13]
	v_readlane_b32 s11, v253, 0
	s_mov_b64 s[8:9], s[14:15]
	s_ashr_i32 s26, s4, 3
	s_cmpk_gt_i32 s26, 0x15ff
	v_mbcnt_lo_u32_b32 v10, -1, 0
	v_mbcnt_hi_u32_b32 v10, -1, v10
	s_cbranch_scc1 .LBB0_653
	s_add_u32 s2, s8, 0x600000
	s_addc_u32 s3, s9, 0
	s_lshr_b32 s4, s26, 29
	s_add_i32 s4, s26, s4
	s_ashr_i32 s5, s4, 3
	s_and_b32 s4, s4, -8
	s_sub_i32 s4, s26, s4
	s_cmp_lt_i32 s4, 0
	s_movk_i32 s10, 0x2c1
	s_cselect_b32 s10, s10, 0x2c0
	s_mul_i32 s4, s4, s10
	s_add_i32 s4, s4, s5
	s_mul_hi_i32 s5, s4, 0x2e8ba2e9
	s_lshr_b32 s10, s5, 31
	s_ashr_i32 s5, s5, 6
	s_add_i32 s5, s5, s10
	s_lshl_b32 s12, s5, 3
	s_mulk_i32 s5, 0x160
	s_sub_i32 s10, s4, s5
	s_bfe_u32 s4, s10, 0x3001c
	s_add_i32 s4, s10, s4
	s_and_b32 s4, s4, 0xfff8
	s_sub_i32 s4, s10, s4
	s_sext_i32_i16 s4, s4
	v_lshl_add_u32 v1, s11, 6, v10
	s_add_i32 s40, s12, s4
	s_movk_i32 s4, 0x100
	v_cmp_gt_i32_e64 s[36:37], s4, v1
	v_ashrrev_i32_e32 v3, 31, v1
	v_lshrrev_b32_e32 v3, 26, v3
	v_add_u32_e32 v3, v1, v3
	v_ashrrev_i32_e32 v11, 6, v3
	v_bfe_i32 v3, v1, 27, 1
	v_lshlrev_b32_e32 v2, 4, v1
	v_lshrrev_b32_e32 v3, 22, v3
	v_add_u32_e32 v3, v2, v3
	v_and_b32_e32 v3, 0xfffffc00, v3
	v_sub_u32_e32 v3, v2, v3
	v_lshrrev_b32_e32 v4, 4, v3
	v_bitop3_b32 v3, v4, v3, 32 bitop3:0x6c
	v_ashrrev_i32_e32 v5, 31, v3
	v_lshrrev_b32_e32 v5, 26, v5
	v_add_u32_e32 v5, v3, v5
	v_readlane_b32 s12, v252, 15
	v_lshlrev_b32_e32 v4, 3, v11
	v_ashrrev_i32_e32 v12, 6, v5
	v_and_b32_e32 v5, 0xc0, v5
	s_ashr_i32 s46, s26, 31
	s_mul_i32 s4, s12, 0x6300000
	v_and_b32_e32 v4, -16, v4
	v_sub_u32_e32 v3, v3, v5
	s_add_u32 s4, s8, s4
	v_add_u32_e32 v4, v12, v4
	v_ashrrev_i16_sdwa v3, v223, sext(v3) dst_sel:DWORD dst_unused:UNUSED_PAD src0_sel:DWORD src1_sel:BYTE_0
	s_addc_u32 s5, s9, 0
	v_lshlrev_b32_e32 v6, 5, v11
	v_bfe_i32 v13, v3, 0, 16
	v_lshlrev_b32_e32 v3, 1, v4
	v_lshrrev_b32_e32 v5, 2, v4
	v_and_b32_e32 v7, 3, v12
	s_mov_b32 s38, 0xfffe0
	s_bitcmp0_b32 s12, 0
	s_mov_b32 s12, 0x1dc00000
	v_and_b32_e32 v6, 32, v6
	v_and_b32_e32 v3, 24, v3
	v_and_b32_e32 v5, 4, v5
	v_and_or_b32 v7, v4, s38, v7
	s_cselect_b32 s12, s12, 0x25c00000
	v_or3_b32 v3, v7, v5, v3
	v_add_lshl_u32 v5, v6, v13, 1
	v_add_u32_e32 v2, 0x2000, v2
	s_add_u32 s47, s8, s12
	v_lshl_add_u32 v132, v3, 12, v5
	v_ashrrev_i32_e32 v3, 31, v2
	s_addc_u32 s48, s9, 0
	v_lshrrev_b32_e32 v3, 22, v3
	s_add_u32 s49, s4, 0x2800000
	s_sext_i32_i16 s4, s10
	v_add_u32_e32 v3, v2, v3
	s_addc_u32 s52, s5, 0
	s_bfe_u32 s4, s4, 0x3001c
	v_ashrrev_i32_e32 v14, 10, v3
	s_add_i32 s10, s10, s4
	v_mul_i32_i24_e32 v3, 0x400, v14
	s_sext_i32_i16 s4, s10
	v_sub_u32_e32 v2, v2, v3
	s_lshr_b32 s10, s4, 3
	v_lshrrev_b32_e32 v3, 4, v2
	v_readlane_b32 s13, v252, 16
	s_bfe_i64 s[4:5], s[10:11], 0x100000
	s_ashr_i32 s41, s40, 31
	v_bitop3_b32 v2, v3, v2, 32 bitop3:0x6c
	s_lshl_b64 s[4:5], s[4:5], 20
	s_lshl_b64 s[12:13], s[40:41], 20
	v_lshl_add_u32 v130, v4, 12, v5
	v_ashrrev_i32_e32 v4, 31, v2
	s_add_u32 s20, s47, s12
	v_lshrrev_b32_e32 v4, 26, v4
	s_addc_u32 s21, s48, s13
	v_add_u32_e32 v4, v2, v4
	s_add_u32 s42, s49, s4
	v_lshlrev_b32_e32 v3, 3, v14
	v_ashrrev_i32_e32 v15, 6, v4
	v_and_b32_e32 v4, 0xc0, v4
	s_addc_u32 s43, s52, s5
	s_ashr_i32 s14, s11, 2
	s_lshl_b32 s41, s11, 10
	v_and_b32_e32 v3, -16, v3
	v_sub_u32_e32 v2, v2, v4
	s_cmp_eq_u32 s14, 1
	v_add_u32_e32 v3, v15, v3
	v_ashrrev_i16_sdwa v2, v223, sext(v2) dst_sel:DWORD dst_unused:UNUSED_PAD src0_sel:DWORD src1_sel:BYTE_0
	s_cselect_b64 s[4:5], -1, 0
	s_add_i32 s53, s41, 0
	v_lshlrev_b32_e32 v5, 5, v14
	v_bfe_i32 v16, v2, 0, 16
	v_lshlrev_b32_e32 v2, 1, v3
	v_lshrrev_b32_e32 v4, 2, v3
	v_and_b32_e32 v6, 3, v15
	s_add_i32 m0, s53, 0x10000
	s_add_i32 s15, s53, 0x12000
	v_and_b32_e32 v5, 32, v5
	v_and_b32_e32 v2, 24, v2
	v_and_b32_e32 v4, 4, v4
	v_and_or_b32 v6, v3, s38, v6
	s_add_u32 s16, s42, 0x80000
	v_or3_b32 v2, v6, v4, v2
	v_add_lshl_u32 v4, v5, v16, 1
	s_waitcnt lgkmcnt(0)
	s_addc_u32 s17, s43, 0
	s_add_i32 s18, s53, 0x14000
	v_lshl_add_u32 v136, v2, 12, v4
	global_load_lds_dwordx4 v132, s[42:43]
	s_mov_b32 m0, s15
	s_add_i32 s19, s53, 0x16000
	global_load_lds_dwordx4 v136, s[42:43]
	s_mov_b32 m0, s18
	s_add_i32 s56, s53, 0x2000
	global_load_lds_dwordx4 v132, s[16:17]
	s_mov_b32 m0, s19
	s_add_u32 s12, s20, 0x80000
	global_load_lds_dwordx4 v136, s[16:17]
	s_mov_b32 m0, s53
	s_addc_u32 s13, s21, 0
	s_add_i32 s57, s53, 0x4000
	v_lshl_add_u32 v134, v3, 12, v4
	global_load_lds_dwordx4 v130, s[20:21]
	s_mov_b32 m0, s56
	s_add_i32 s64, s53, 0x6000
	global_load_lds_dwordx4 v134, s[20:21]
	s_mov_b32 m0, s57
	v_mov_b32_e32 v133, v0
	global_load_lds_dwordx4 v130, s[12:13]
	s_mov_b32 m0, s64
	v_mov_b32_e32 v137, v0
	global_load_lds_dwordx4 v134, s[12:13]
	v_mov_b32_e32 v131, v0
	v_mov_b32_e32 v135, v0
	s_and_saveexec_b64 vcc, s[36:37]
	s_cbranch_execz .Lprep_1
	v_lshl_add_u32 v90, s40, 8, v1
	v_ashrrev_i32_e32 v91, 31, v90
	v_lshlrev_b64 v[90:91], 7, v[90:91]
	v_lshl_add_u64 v[108:109], s[2:3], 0, v[90:91]
	global_load_dwordx4 v[90:93], v[108:109], off offset:48
	global_load_dwordx4 v[94:97], v[108:109], off offset:32
	global_load_dwordx4 v[100:103], v[108:109], off
	global_load_dwordx4 v[104:107], v[108:109], off offset:16
	global_load_dwordx4 v[114:117], v[108:109], off offset:112
	global_load_dwordx4 v[118:121], v[108:109], off offset:96
	global_load_dwordx4 v[122:125], v[108:109], off offset:80
	global_load_dwordx4 v[126:129], v[108:109], off offset:64
	s_waitcnt vmcnt(4)
	v_pk_add_f32 v[102:103], v[102:103], v[106:107]
	v_pk_add_f32 v[100:101], v[100:101], v[104:105]
	v_pk_add_f32 v[96:97], v[102:103], v[96:97]
	v_pk_add_f32 v[94:95], v[100:101], v[94:95]
	v_pk_add_f32 v[110:111], v[96:97], v[92:93]
	v_pk_add_f32 v[112:113], v[94:95], v[90:91]
	s_waitcnt vmcnt(0)
	v_pk_add_f32 v[128:129], v[110:111], v[128:129]
	v_pk_add_f32 v[126:127], v[112:113], v[126:127]
	v_pk_add_f32 v[124:125], v[128:129], v[124:125]
	v_pk_add_f32 v[122:123], v[126:127], v[122:123]
	v_pk_add_f32 v[120:121], v[124:125], v[120:121]
	v_pk_add_f32 v[118:119], v[122:123], v[118:119]
	v_pk_add_f32 v[116:117], v[120:121], v[116:117]
	v_pk_add_f32 v[114:115], v[118:119], v[114:115]
	s_nop 0
	v_pk_mov_b32 v[118:119], v[114:115], v[116:117] op_sel:[1,0]
	v_mov_b32_e32 v115, v117
	v_pk_add_f32 v[114:115], v[118:119], v[114:115]
	s_nop 0
	v_add_f32_e32 v114, v114, v115
	v_fmamk_f32 v114, v114, 0x3a000000, v221
	v_rsq_f32_e32 v114, v114
	v_lshl_add_u32 v115, v1, 2, 0
	v_add_u32_e32 v115, 0x20000, v115
	ds_write_b32 v115, v114
.Lprep_1:
	s_or_b64 exec, exec, vcc
	s_cmp_lg_u32 s14, 1
	v_lshl_add_u64 v[8:9], s[42:43], 0, v[132:133]
	v_lshl_add_u64 v[6:7], s[42:43], 0, v[136:137]
	v_lshl_add_u64 v[4:5], s[20:21], 0, v[130:131]
	v_lshl_add_u64 v[2:3], s[20:21], 0, v[134:135]
	s_cbranch_scc1 .LBB0_635
	s_barrier

; __device__ __forceinline__ void rs_prep(const float* ss, int pm, int parity, PG8_LAS unsigned char* lds, int tid) {
;     if (tid < 256) {
;         const f32x4* p = (const f32x4*)(ss + (size_t)(pm * BM + tid) * 32);
;         f32x4 s = p[0];
; #pragma unroll
;         for (int j = 1; j < 8; ++j) s += p[j];
;         const float tot = (s[0] + s[1]) + (s[2] + s[3]);
;         *(PG8_LAS float*)(lds + RS_OFF + parity * 1024 + tid * 4) = __builtin_amdgcn_rsqf(tot * (1.0f / 2048.0f) + 1e-6f);
;     }
;     asm volatile("s_waitcnt lgkmcnt(0)" ::: "memory");
; }
; template <class Epi, class Sched, bool ALIGN_EPI = false, bool SP2 = false>
; __device__ __forceinline__ void gemm_phase(PG8_LAS unsigned char* lds, const Gemm g, const Sched& S, const Epi& E, const int wave_id) {
;     ...
;     for (int i = 0; i < 2; ++i) { int R, C; stage_rc(tid * 16 + i * 8192, R, C); const int Rb = Epi::PERM ? ((R & ~31) + perm32(R & 31)) : R;
;         voffA[i] = (unsigned)(R * K + C) * 2u; voffB[i] = (unsigned)(Rb * K + C) * 2u; }
;     const size_t kstep = (size_t)(BK * 2);
;     const size_t hstep = (size_t)HALF * K * 2;
;     const size_t tstep = 2 * hstep;
;     const unsigned ldsw = (unsigned)wid * 1024u;
;     const int aoff = lds_byte(wr * 64 + fr, fq * 8), boff = lds_byte(wc * 32 + fr, fq * 8);
;     ...
;     Unit cur, nxt; int ui = 0, tp = 0;
;     if (!S.next(0, cur)) return;
;     f32x4 acc[2][2][4][2];
; #pragma unroll
;     for (int a = 0; a < 2; ++a)
; #pragma unroll
;         for (int b = 0; b < 2; ++b)
; #pragma unroll
;             for (int m = 0; m < 4; ++m)
; #pragma unroll
;                 for (int n = 0; n < 2; ++n) acc[a][b][m][n] = (f32x4){0.f, 0.f, 0.f, 0.f};
;     bf16x8 At[4][2], B0[2][2], B1[2][2];
;     const char* cA = (const char*)g.A + (size_t)cur.lm * tstep; const char* cB = (const char*)g.Bt + (size_t)cur.ln * tstep;
;     if constexpr (Epi::HAS_PREP) E.prep(cur, 0, lds, tid);
;     S.a_ready(cur);
;     if constexpr (SP2) {
;         PG8_STAGE(PG8_SB(0, 0), cB, voffB); PG8_STAGE(PG8_SB(0, 1), cB + hstep, voffB); PG8_STAGE(PG8_SA(0, 0), cA, voffA); PG8_STAGE(PG8_SA(0, 1), cA + hstep, voffA);
;         if (wr == 1) PG8_BAR;
;         PG8_WAIT_V(2); PG8_BAR;
;         PG8_STAGE(PG8_SB(1, 0), cB + kstep, voffB); PG8_STAGE(PG8_SA(1, 0), cA + kstep, voffA); PG8_STAGE(PG8_SB(1, 1), cB + hstep + kstep, voffB);
;         PG8_WAIT_V(6); PG8_BAR;
.LBB0_889:
	s_andn2_b64 vcc, exec, s[4:5]
	s_cbranch_vccnz .LBB0_932
	s_add_u32 s4, s14, 0xa00000
	v_lshl_add_u32 v1, s18, 6, v10
	s_movk_i32 s8, 0x100
	s_addc_u32 s5, s15, 0
	v_cmp_gt_i32_e64 s[36:37], s8, v1
	v_ashrrev_i32_e32 v3, 31, v1
	v_lshrrev_b32_e32 v3, 26, v3
	v_add_u32_e32 v3, v1, v3
	v_ashrrev_i32_e32 v11, 6, v3
	v_bfe_i32 v3, v1, 27, 1
	v_lshlrev_b32_e32 v2, 4, v1
	v_lshrrev_b32_e32 v3, 22, v3
	v_add_u32_e32 v3, v2, v3
	v_and_b32_e32 v3, 0xfffffc00, v3
	v_sub_u32_e32 v3, v2, v3
	v_lshrrev_b32_e32 v4, 4, v3
	v_readlane_b32 s0, v252, 15
	v_bitop3_b32 v3, v4, v3, 32 bitop3:0x6c
	s_mul_i32 s8, s0, 0x6300000
	v_ashrrev_i32_e32 v5, 31, v3
	s_add_u32 s19, s14, s8
	v_lshrrev_b32_e32 v5, 26, v5
	s_addc_u32 s20, s15, 0
	v_add_u32_e32 v5, v3, v5
	s_bitcmp0_b32 s0, 0
	v_lshlrev_b32_e32 v4, 3, v11
	v_ashrrev_i32_e32 v12, 6, v5
	v_and_b32_e32 v5, 0xc0, v5
	s_cselect_b64 s[16:17], -1, 0
	v_and_b32_e32 v4, -16, v4
	v_sub_u32_e32 v3, v3, v5
	s_and_b64 s[8:9], s[16:17], exec
	s_mov_b32 s0, 0x1dc00000
	v_add_u32_e32 v4, v12, v4
	v_ashrrev_i16_sdwa v3, v223, sext(v3) dst_sel:DWORD dst_unused:UNUSED_PAD src0_sel:DWORD src1_sel:BYTE_0
	s_cselect_b32 s8, s0, 0x25c00000
	v_lshlrev_b32_e32 v6, 5, v11
	v_bfe_i32 v13, v3, 0, 16
	v_lshlrev_b32_e32 v3, 1, v4
	v_lshrrev_b32_e32 v5, 2, v4
	v_and_b32_e32 v7, 3, v12
	s_mov_b32 s0, 0xfffe0
	v_and_b32_e32 v6, 32, v6
	v_and_b32_e32 v3, 24, v3
	v_and_b32_e32 v5, 4, v5
	v_and_or_b32 v7, v4, s0, v7
	v_or3_b32 v3, v7, v5, v3
	v_add_lshl_u32 v5, v6, v13, 1
	v_add_u32_e32 v2, 0x2000, v2
	v_lshl_add_u32 v208, v3, 12, v5
	v_ashrrev_i32_e32 v3, 31, v2
	v_lshrrev_b32_e32 v3, 22, v3
	v_add_u32_e32 v3, v2, v3
	v_ashrrev_i32_e32 v14, 10, v3
	v_mul_i32_i24_e32 v3, 0x400, v14
	s_add_u32 s8, s14, s8
	v_sub_u32_e32 v2, v2, v3
	s_addc_u32 s9, s15, 0
	v_lshrrev_b32_e32 v3, 4, v2
	s_add_u32 s65, s19, 0x6a00000
	v_bitop3_b32 v2, v3, v2, 32 bitop3:0x6c
	s_addc_u32 s68, s20, 0
	v_lshl_add_u32 v206, v4, 12, v5
	v_ashrrev_i32_e32 v4, 31, v2
	s_add_u32 s46, s8, s12
	v_lshrrev_b32_e32 v4, 26, v4
	s_addc_u32 s47, s9, s13
	v_add_u32_e32 v4, v2, v4
	s_add_u32 s52, s65, s10
	v_lshlrev_b32_e32 v3, 3, v14
	v_ashrrev_i32_e32 v15, 6, v4
	v_and_b32_e32 v4, 0xc0, v4
	s_addc_u32 s53, s68, s11
	s_ashr_i32 s19, s18, 2
	s_lshl_b32 s69, s18, 10
	v_and_b32_e32 v3, -16, v3
	v_sub_u32_e32 v2, v2, v4
	s_cmp_eq_u32 s19, 1
	v_add_u32_e32 v3, v15, v3
	v_ashrrev_i16_sdwa v2, v223, sext(v2) dst_sel:DWORD dst_unused:UNUSED_PAD src0_sel:DWORD src1_sel:BYTE_0
	s_cselect_b64 s[10:11], -1, 0
	s_add_i32 s70, s69, 0
	v_lshlrev_b32_e32 v5, 5, v14
	v_bfe_i32 v16, v2, 0, 16
	v_lshlrev_b32_e32 v2, 1, v3
	v_lshrrev_b32_e32 v4, 2, v3
	v_and_b32_e32 v6, 3, v15
	s_add_i32 m0, s70, 0x10000
	s_add_i32 s38, s70, 0x12000
	v_and_b32_e32 v5, 32, v5
	v_and_b32_e32 v2, 24, v2
	v_and_b32_e32 v4, 4, v4
	v_and_or_b32 v6, v3, s0, v6
	s_add_u32 s20, s52, 0x80000
	v_or3_b32 v2, v6, v4, v2
	v_add_lshl_u32 v4, v5, v16, 1
	s_waitcnt lgkmcnt(0)
	s_addc_u32 s21, s53, 0
	s_add_i32 s39, s70, 0x14000
	v_lshl_add_u32 v212, v2, 12, v4
	global_load_lds_dwordx4 v208, s[52:53]
	s_mov_b32 m0, s38
	s_add_i32 s40, s70, 0x16000
	global_load_lds_dwordx4 v212, s[52:53]
	s_mov_b32 m0, s39
	s_add_i32 s71, s70, 0x2000
	global_load_lds_dwordx4 v208, s[20:21]
	s_mov_b32 m0, s40
	s_add_u32 s12, s46, 0x80000
	global_load_lds_dwordx4 v212, s[20:21]
	s_mov_b32 m0, s70
	s_addc_u32 s13, s47, 0
	s_add_i32 s72, s70, 0x4000
	v_lshl_add_u32 v210, v3, 12, v4
	global_load_lds_dwordx4 v206, s[46:47]
	s_mov_b32 m0, s71
	s_add_i32 s73, s70, 0x6000
	global_load_lds_dwordx4 v210, s[46:47]
	s_mov_b32 m0, s72
	v_mov_b32_e32 v209, v0
	global_load_lds_dwordx4 v206, s[12:13]
	s_mov_b32 m0, s73
	v_mov_b32_e32 v213, v0
	global_load_lds_dwordx4 v210, s[12:13]
	v_mov_b32_e32 v207, v0
	v_mov_b32_e32 v211, v0
	s_and_saveexec_b64 vcc, s[36:37]
	s_cbranch_execz .Lprep_2
	v_lshl_add_u32 v74, s48, 8, v1
	v_ashrrev_i32_e32 v75, 31, v74
	v_lshlrev_b64 v[74:75], 7, v[74:75]
	v_lshl_add_u64 v[92:93], s[4:5], 0, v[74:75]
	global_load_dwordx4 v[74:77], v[92:93], off offset:48
	global_load_dwordx4 v[78:81], v[92:93], off offset:32
	global_load_dwordx4 v[84:87], v[92:93], off
	global_load_dwordx4 v[88:91], v[92:93], off offset:16
	global_load_dwordx4 v[98:101], v[92:93], off offset:112
	global_load_dwordx4 v[102:105], v[92:93], off offset:96
	global_load_dwordx4 v[106:109], v[92:93], off offset:80
	global_load_dwordx4 v[110:113], v[92:93], off offset:64
	s_waitcnt vmcnt(4)
	v_pk_add_f32 v[86:87], v[86:87], v[90:91]
	v_pk_add_f32 v[84:85], v[84:85], v[88:89]
	v_pk_add_f32 v[80:81], v[86:87], v[80:81]
	v_pk_add_f32 v[78:79], v[84:85], v[78:79]
	v_pk_add_f32 v[94:95], v[80:81], v[76:77]
	v_pk_add_f32 v[96:97], v[78:79], v[74:75]
	s_waitcnt vmcnt(0)
	v_pk_add_f32 v[112:113], v[94:95], v[112:113]
	v_pk_add_f32 v[110:111], v[96:97], v[110:111]
	v_pk_add_f32 v[108:109], v[112:113], v[108:109]
	v_pk_add_f32 v[106:107], v[110:111], v[106:107]
	v_pk_add_f32 v[104:105], v[108:109], v[104:105]
	v_pk_add_f32 v[102:103], v[106:107], v[102:103]
	v_pk_add_f32 v[100:101], v[104:105], v[100:101]
	v_pk_add_f32 v[98:99], v[102:103], v[98:99]
	s_nop 0
	v_pk_mov_b32 v[102:103], v[98:99], v[100:101] op_sel:[1,0]
	v_mov_b32_e32 v99, v101
	v_pk_add_f32 v[98:99], v[102:103], v[98:99]
	s_nop 0
	v_add_f32_e32 v98, v98, v99
	v_fmamk_f32 v98, v98, 0x3a000000, v221
	v_rsq_f32_e32 v98, v98
	v_lshl_add_u32 v99, v1, 2, 0
	v_add_u32_e32 v99, 0x20000, v99
	ds_write_b32 v99, v98
.Lprep_2:
	s_or_b64 exec, exec, vcc
	s_cmp_lg_u32 s19, 1
	v_lshl_add_u64 v[8:9], s[52:53], 0, v[208:209]
	v_lshl_add_u64 v[6:7], s[52:53], 0, v[212:213]
	v_lshl_add_u64 v[4:5], s[46:47], 0, v[206:207]
	v_lshl_add_u64 v[2:3], s[46:47], 0, v[210:211]
	v_readlane_b32 s1, v252, 16
	s_cbranch_scc1 .LBB0_894
	s_barrier
